# wt3_pz + GEMM unit boundaries without the two alignment barriers (leading half epilogue beside the trailing half's last MFMA block)
# baseline (speedup 1.0000x reference)
.Lmy_sk2:
	s_waitcnt lgkmcnt(0)
	s_setprio 1
	s_barrier
	v_mfma_f32_16x16x32_bf16 v[62:65], v[132:135], v[184:187], v[62:65]
	v_mfma_f32_16x16x32_bf16 v[58:61], v[140:143], v[184:187], v[58:61]
	v_mfma_f32_16x16x32_bf16 v[54:57], v[132:135], v[192:195], v[54:57]
	v_mfma_f32_16x16x32_bf16 v[46:49], v[140:143], v[192:195], v[46:49]
	v_mfma_f32_16x16x32_bf16 v[38:41], v[132:135], v[208:211], v[38:41]
	v_mfma_f32_16x16x32_bf16 v[30:33], v[140:143], v[208:211], v[30:33]
	v_mfma_f32_16x16x32_bf16 v[22:25], v[132:135], v[216:219], v[22:25]
	v_mfma_f32_16x16x32_bf16 v[14:17], v[140:143], v[216:219], v[14:17]
	v_mfma_f32_16x16x32_bf16 v[62:65], v[136:139], v[188:191], v[62:65]
	v_mfma_f32_16x16x32_bf16 v[58:61], v[144:147], v[188:191], v[58:61]
	v_mfma_f32_16x16x32_bf16 v[54:57], v[136:139], v[204:207], v[54:57]
	v_mfma_f32_16x16x32_bf16 v[46:49], v[144:147], v[204:207], v[46:49]
	v_mfma_f32_16x16x32_bf16 v[38:41], v[136:139], v[212:215], v[38:41]
	v_mfma_f32_16x16x32_bf16 v[30:33], v[144:147], v[212:215], v[30:33]
	v_mfma_f32_16x16x32_bf16 v[22:25], v[136:139], v[220:223], v[22:25]
	v_mfma_f32_16x16x32_bf16 v[14:17], v[144:147], v[220:223], v[14:17]
	s_setprio 0
	s_setprio 1
	v_mfma_f32_16x16x32_bf16 v[50:53], v[156:159], v[184:187], v[50:53]
	v_mfma_f32_16x16x32_bf16 v[42:45], v[164:167], v[184:187], v[42:45]
	v_mfma_f32_16x16x32_bf16 v[34:37], v[156:159], v[192:195], v[34:37]
	v_mfma_f32_16x16x32_bf16 v[26:29], v[164:167], v[192:195], v[26:29]
	v_mfma_f32_16x16x32_bf16 v[18:21], v[156:159], v[208:211], v[18:21]
	v_mfma_f32_16x16x32_bf16 v[10:13], v[164:167], v[208:211], v[10:13]
	v_mfma_f32_16x16x32_bf16 v[6:9], v[156:159], v[216:219], v[6:9]
	v_mfma_f32_16x16x32_bf16 v[2:5], v[164:167], v[216:219], v[2:5]
	v_mfma_f32_16x16x32_bf16 v[50:53], v[160:163], v[188:191], v[50:53]
	v_mfma_f32_16x16x32_bf16 v[42:45], v[180:183], v[188:191], v[42:45]
	v_mfma_f32_16x16x32_bf16 v[34:37], v[160:163], v[204:207], v[34:37]
	v_mfma_f32_16x16x32_bf16 v[26:29], v[180:183], v[204:207], v[26:29]
	v_mfma_f32_16x16x32_bf16 v[18:21], v[160:163], v[212:215], v[18:21]
	v_mfma_f32_16x16x32_bf16 v[10:13], v[180:183], v[212:215], v[10:13]
	v_mfma_f32_16x16x32_bf16 v[6:9], v[160:163], v[220:223], v[6:9]
	v_mfma_f32_16x16x32_bf16 v[2:5], v[180:183], v[220:223], v[2:5]
	s_setprio 0
	s_barrier
	s_add_i32 s4, 0, 0x18000
	s_add_i32 s5, 0, 0x1c000
	v_add_u32_e32 v144, s4, v175
	v_add_u32_e32 v170, s5, v175
	ds_read_b128 v[132:135], v144
	ds_read_b128 v[136:139], v144 offset:1024
	ds_read_b128 v[140:143], v144 offset:2048
	ds_read_b128 v[144:147], v144 offset:3072
	ds_read_b128 v[156:159], v170
	ds_read_b128 v[160:163], v170 offset:1024
	ds_read_b128 v[164:167], v170 offset:2048
	ds_read_b128 v[180:183], v170 offset:3072
	s_add_u32 s44, s70, 0x40000
	s_addc_u32 s45, s71, 0
	v_lshl_add_u64 v[202:203], s[44:45], 0, v[98:99]
	s_add_i32 m0, s94, 0x4000
	ds_read_b128 v[184:187], v179 offset:32768
	ds_read_b128 v[188:191], v179 offset:33792
	ds_read_b128 v[192:195], v179 offset:34816
	ds_read_b128 v[204:207], v179 offset:35840
	ds_read_b128 v[208:211], v179 offset:36864
	ds_read_b128 v[212:215], v179 offset:37888
	ds_read_b128 v[216:219], v179 offset:38912
	ds_read_b128 v[220:223], v179 offset:39936
	global_load_lds_dwordx4 v[202:203], off
	v_lshl_add_u64 v[202:203], s[44:45], 0, v[150:151]
	s_add_i32 m0, s94, 0x6000
	s_nop 0
	global_load_lds_dwordx4 v[202:203], off
	s_waitcnt vmcnt(8)
	s_waitcnt lgkmcnt(0)
	s_setprio 1
	s_barrier
	v_mfma_f32_16x16x32_bf16 v[128:131], v[132:135], v[184:187], v[128:131]
	v_mfma_f32_16x16x32_bf16 v[124:127], v[140:143], v[184:187], v[124:127]
	v_mfma_f32_16x16x32_bf16 v[120:123], v[132:135], v[192:195], v[120:123]
	v_mfma_f32_16x16x32_bf16 v[112:115], v[140:143], v[192:195], v[112:115]
	v_mfma_f32_16x16x32_bf16 v[104:107], v[132:135], v[208:211], v[104:107]
	v_mfma_f32_16x16x32_bf16 v[94:97], v[140:143], v[208:211], v[94:97]
	v_mfma_f32_16x16x32_bf16 v[86:89], v[132:135], v[216:219], v[86:89]
	v_mfma_f32_16x16x32_bf16 v[78:81], v[140:143], v[216:219], v[78:81]
	v_mfma_f32_16x16x32_bf16 v[128:131], v[136:139], v[188:191], v[128:131]
	v_mfma_f32_16x16x32_bf16 v[124:127], v[144:147], v[188:191], v[124:127]
	v_mfma_f32_16x16x32_bf16 v[120:123], v[136:139], v[204:207], v[120:123]
	v_mfma_f32_16x16x32_bf16 v[112:115], v[144:147], v[204:207], v[112:115]
	v_mfma_f32_16x16x32_bf16 v[104:107], v[136:139], v[212:215], v[104:107]
	v_mfma_f32_16x16x32_bf16 v[94:97], v[144:147], v[212:215], v[94:97]
	v_mfma_f32_16x16x32_bf16 v[86:89], v[136:139], v[220:223], v[86:89]
	v_mfma_f32_16x16x32_bf16 v[78:81], v[144:147], v[220:223], v[78:81]
	s_setprio 0
	s_setprio 1
	v_mfma_f32_16x16x32_bf16 v[116:119], v[156:159], v[184:187], v[116:119]
	v_mfma_f32_16x16x32_bf16 v[108:111], v[164:167], v[184:187], v[108:111]
	v_mfma_f32_16x16x32_bf16 v[100:103], v[156:159], v[192:195], v[100:103]
	v_mfma_f32_16x16x32_bf16 v[90:93], v[164:167], v[192:195], v[90:93]
	v_mfma_f32_16x16x32_bf16 v[82:85], v[156:159], v[208:211], v[82:85]
	v_mfma_f32_16x16x32_bf16 v[74:77], v[164:167], v[208:211], v[74:77]
	v_mfma_f32_16x16x32_bf16 v[70:73], v[156:159], v[216:219], v[70:73]
	v_mfma_f32_16x16x32_bf16 v[66:69], v[164:167], v[216:219], v[66:69]
	v_mfma_f32_16x16x32_bf16 v[116:119], v[160:163], v[188:191], v[116:119]
	v_mfma_f32_16x16x32_bf16 v[108:111], v[180:183], v[188:191], v[108:111]
	v_mfma_f32_16x16x32_bf16 v[100:103], v[160:163], v[204:207], v[100:103]
	v_mfma_f32_16x16x32_bf16 v[90:93], v[180:183], v[204:207], v[90:93]
	v_mfma_f32_16x16x32_bf16 v[82:85], v[160:163], v[212:215], v[82:85]
	v_mfma_f32_16x16x32_bf16 v[74:77], v[180:183], v[212:215], v[74:77]
	v_mfma_f32_16x16x32_bf16 v[70:73], v[160:163], v[220:223], v[70:73]
	v_mfma_f32_16x16x32_bf16 v[66:69], v[180:183], v[220:223], v[66:69]
	s_setprio 0
	s_barrier
	s_add_i32 s4, s4, s77
	v_lshl_add_u64 v[168:169], v[168:169], 0, s[42:43]
	s_mov_b32 m0, s4
	ds_read_b128 v[184:187], v179 offset:49152
	ds_read_b128 v[188:191], v179 offset:50176
	ds_read_b128 v[192:195], v179 offset:51200
	ds_read_b128 v[204:207], v179 offset:52224
	ds_read_b128 v[208:211], v179 offset:53248
	ds_read_b128 v[212:215], v179 offset:54272
	ds_read_b128 v[216:219], v179 offset:55296
	ds_read_b128 v[220:223], v179 offset:56320
	global_load_lds_dwordx4 v[168:169], off
	s_add_i32 m0, s4, 0x2000
	s_add_u32 s44, s68, 0x40080
	v_lshl_add_u64 v[168:169], v[172:173], 0, s[42:43]
	s_addc_u32 s45, s69, 0
	s_add_i32 s4, s5, s77
	global_load_lds_dwordx4 v[168:169], off
	v_lshl_add_u64 v[168:169], s[44:45], 0, v[148:149]
	s_mov_b32 m0, s4
	s_nop 0
	global_load_lds_dwordx4 v[168:169], off
	v_lshl_add_u64 v[168:169], s[44:45], 0, v[152:153]
	s_add_i32 m0, s4, 0x2000
	s_nop 0
	global_load_lds_dwordx4 v[168:169], off
	v_lshl_add_u64 v[168:169], v[176:177], 0, s[42:43]
	s_add_i32 m0, s94, 0x8000
	s_nop 0
	global_load_lds_dwordx4 v[168:169], off
	v_lshl_add_u64 v[168:169], v[200:201], 0, s[42:43]
	s_add_i32 m0, s94, 0xa000
	s_nop 0
	global_load_lds_dwordx4 v[168:169], off
	s_waitcnt vmcnt(8)
	s_waitcnt lgkmcnt(0)
	s_setprio 1
	s_barrier
	v_mfma_f32_16x16x32_bf16 v[62:65], v[132:135], v[184:187], v[62:65]
	v_mfma_f32_16x16x32_bf16 v[58:61], v[140:143], v[184:187], v[58:61]
	v_mfma_f32_16x16x32_bf16 v[54:57], v[132:135], v[192:195], v[54:57]
	v_mfma_f32_16x16x32_bf16 v[46:49], v[140:143], v[192:195], v[46:49]
	v_mfma_f32_16x16x32_bf16 v[38:41], v[132:135], v[208:211], v[38:41]
	v_mfma_f32_16x16x32_bf16 v[30:33], v[140:143], v[208:211], v[30:33]
	v_mfma_f32_16x16x32_bf16 v[22:25], v[132:135], v[216:219], v[22:25]
	v_mfma_f32_16x16x32_bf16 v[14:17], v[140:143], v[216:219], v[14:17]
	v_mfma_f32_16x16x32_bf16 v[62:65], v[136:139], v[188:191], v[62:65]
	v_mfma_f32_16x16x32_bf16 v[58:61], v[144:147], v[188:191], v[58:61]
	v_mfma_f32_16x16x32_bf16 v[54:57], v[136:139], v[204:207], v[54:57]
	v_mfma_f32_16x16x32_bf16 v[46:49], v[144:147], v[204:207], v[46:49]
	v_mfma_f32_16x16x32_bf16 v[38:41], v[136:139], v[212:215], v[38:41]
	v_mfma_f32_16x16x32_bf16 v[30:33], v[144:147], v[212:215], v[30:33]
	v_mfma_f32_16x16x32_bf16 v[22:25], v[136:139], v[220:223], v[22:25]
	v_mfma_f32_16x16x32_bf16 v[14:17], v[144:147], v[220:223], v[14:17]
	s_setprio 0
	s_setprio 1
	v_mfma_f32_16x16x32_bf16 v[50:53], v[156:159], v[184:187], v[50:53]
	v_mfma_f32_16x16x32_bf16 v[42:45], v[164:167], v[184:187], v[42:45]
	v_mfma_f32_16x16x32_bf16 v[34:37], v[156:159], v[192:195], v[34:37]
	v_mfma_f32_16x16x32_bf16 v[26:29], v[164:167], v[192:195], v[26:29]
	v_mfma_f32_16x16x32_bf16 v[18:21], v[156:159], v[208:211], v[18:21]
	v_mfma_f32_16x16x32_bf16 v[10:13], v[164:167], v[208:211], v[10:13]
	v_mfma_f32_16x16x32_bf16 v[6:9], v[156:159], v[216:219], v[6:9]
	v_mfma_f32_16x16x32_bf16 v[2:5], v[164:167], v[216:219], v[2:5]
	v_mfma_f32_16x16x32_bf16 v[50:53], v[160:163], v[188:191], v[50:53]
	v_mfma_f32_16x16x32_bf16 v[42:45], v[180:183], v[188:191], v[42:45]
	v_mfma_f32_16x16x32_bf16 v[34:37], v[160:163], v[204:207], v[34:37]
	v_mfma_f32_16x16x32_bf16 v[26:29], v[180:183], v[204:207], v[26:29]
	v_mfma_f32_16x16x32_bf16 v[18:21], v[160:163], v[212:215], v[18:21]
	v_mfma_f32_16x16x32_bf16 v[10:13], v[180:183], v[212:215], v[10:13]
	v_mfma_f32_16x16x32_bf16 v[6:9], v[160:163], v[220:223], v[6:9]
	v_mfma_f32_16x16x32_bf16 v[2:5], v[180:183], v[220:223], v[2:5]
	s_setprio 0
	s_barrier
	s_mov_b32 s100, 0
	s_add_i32 s93, s93, 2
	s_add_u32 s0, s0, 0x100
	s_addc_u32 s1, s1, 0
	s_add_u32 s91, s91, 0x100
	s_addc_u32 s92, s92, 0
	s_cmp_gt_u32 s93, 13
	s_cbranch_scc0 .LBB0_322
	s_mov_b32 s100, 1
	s_and_b64 vcc, exec, s[14:15]
	s_cbranch_vccz .LBB0_325
	s_nop 0

.Lmy_wt_g1_15r:
	s_cbranch_vccnz .LBB0_316
	s_andn2_b64 vcc, exec, s[20:21]
	s_cbranch_vccnz .LBB0_315
	s_nop 0
	s_branch .LBB0_315

.LBB0_328:
	s_waitcnt vmcnt(0)
	v_readlane_b32 s8, v255, 31
	v_readlane_b32 s74, v255, 33
	v_readlane_b32 s70, v255, 37
	v_readlane_b32 s9, v255, 32
	v_readlane_b32 s75, v255, 34
	v_readlane_b32 s77, v255, 36
	v_readlane_b32 s71, v255, 38
	s_mov_b64 s[78:79], 0x10000
	s_and_b64 vcc, exec, s[14:15]
	s_cbranch_vccz .Lmy_ua_g1
	s_barrier
.Lmy_ua_g1:
	s_barrier

.Lmy_sk4:
	s_waitcnt lgkmcnt(0)
	s_setprio 1
	s_barrier
	v_mfma_f32_16x16x32_bf16 v[62:65], v[90:93], v[164:167], v[62:65]
	v_mfma_f32_16x16x32_bf16 v[58:61], v[100:103], v[164:167], v[58:61]
	v_mfma_f32_16x16x32_bf16 v[46:49], v[90:93], v[172:175], v[46:49]
	v_mfma_f32_16x16x32_bf16 v[42:45], v[100:103], v[172:175], v[42:45]
	v_mfma_f32_16x16x32_bf16 v[30:33], v[90:93], v[180:183], v[30:33]
	v_mfma_f32_16x16x32_bf16 v[26:29], v[100:103], v[180:183], v[26:29]
	v_mfma_f32_16x16x32_bf16 v[14:17], v[90:93], v[188:191], v[14:17]
	v_mfma_f32_16x16x32_bf16 v[10:13], v[100:103], v[188:191], v[10:13]
	v_mfma_f32_16x16x32_bf16 v[62:65], v[94:97], v[168:171], v[62:65]
	v_mfma_f32_16x16x32_bf16 v[58:61], v[104:107], v[168:171], v[58:61]
	v_mfma_f32_16x16x32_bf16 v[46:49], v[94:97], v[176:179], v[46:49]
	v_mfma_f32_16x16x32_bf16 v[42:45], v[104:107], v[176:179], v[42:45]
	v_mfma_f32_16x16x32_bf16 v[30:33], v[94:97], v[184:187], v[30:33]
	v_mfma_f32_16x16x32_bf16 v[26:29], v[104:107], v[184:187], v[26:29]
	v_mfma_f32_16x16x32_bf16 v[14:17], v[94:97], v[192:195], v[14:17]
	v_mfma_f32_16x16x32_bf16 v[10:13], v[104:107], v[192:195], v[10:13]
	s_setprio 0
	s_setprio 1
	v_mfma_f32_16x16x32_bf16 v[54:57], v[108:111], v[164:167], v[54:57]
	v_mfma_f32_16x16x32_bf16 v[50:53], v[120:123], v[164:167], v[50:53]
	v_mfma_f32_16x16x32_bf16 v[38:41], v[108:111], v[172:175], v[38:41]
	v_mfma_f32_16x16x32_bf16 v[34:37], v[120:123], v[172:175], v[34:37]
	v_mfma_f32_16x16x32_bf16 v[22:25], v[108:111], v[180:183], v[22:25]
	v_mfma_f32_16x16x32_bf16 v[18:21], v[120:123], v[180:183], v[18:21]
	v_mfma_f32_16x16x32_bf16 v[6:9], v[108:111], v[188:191], v[6:9]
	v_mfma_f32_16x16x32_bf16 v[2:5], v[120:123], v[188:191], v[2:5]
	v_mfma_f32_16x16x32_bf16 v[54:57], v[112:115], v[168:171], v[54:57]
	v_mfma_f32_16x16x32_bf16 v[50:53], v[128:131], v[168:171], v[50:53]
	v_mfma_f32_16x16x32_bf16 v[38:41], v[112:115], v[176:179], v[38:41]
	v_mfma_f32_16x16x32_bf16 v[34:37], v[128:131], v[176:179], v[34:37]
	v_mfma_f32_16x16x32_bf16 v[22:25], v[112:115], v[184:187], v[22:25]
	v_mfma_f32_16x16x32_bf16 v[18:21], v[128:131], v[184:187], v[18:21]
	v_mfma_f32_16x16x32_bf16 v[6:9], v[112:115], v[192:195], v[6:9]
	v_mfma_f32_16x16x32_bf16 v[2:5], v[128:131], v[192:195], v[2:5]
	s_setprio 0
	s_barrier
	s_add_i32 s6, 0, 0x18000
	s_add_i32 s7, 0, 0x1c000
	v_add_u32_e32 v104, s6, v239
	v_add_u32_e32 v128, s7, v239
	ds_read_b128 v[90:93], v104
	ds_read_b128 v[94:97], v104 offset:1024
	ds_read_b128 v[100:103], v104 offset:2048
	ds_read_b128 v[104:107], v104 offset:3072
	ds_read_b128 v[108:111], v128
	ds_read_b128 v[112:115], v128 offset:1024
	ds_read_b128 v[120:123], v128 offset:2048
	ds_read_b128 v[128:131], v128 offset:3072
	s_add_u32 s4, s74, 0x40000
	s_addc_u32 s5, s75, 0
	v_lshl_add_u64 v[214:215], s[4:5], 0, v[98:99]
	s_add_i32 m0, s44, 0x4000
	ds_read_b128 v[164:167], v241 offset:32768
	ds_read_b128 v[168:171], v241 offset:33792
	ds_read_b128 v[172:175], v241 offset:34816
	ds_read_b128 v[176:179], v241 offset:35840
	ds_read_b128 v[180:183], v241 offset:36864
	ds_read_b128 v[184:187], v241 offset:37888
	ds_read_b128 v[188:191], v241 offset:38912
	ds_read_b128 v[192:195], v241 offset:39936
	global_load_lds_dwordx4 v[214:215], off
	v_lshl_add_u64 v[214:215], s[4:5], 0, v[206:207]
	s_add_i32 m0, s44, 0x6000
	s_nop 0
	global_load_lds_dwordx4 v[214:215], off
	s_waitcnt vmcnt(8)
	s_waitcnt lgkmcnt(0)
	s_setprio 1
	s_barrier
	v_mfma_f32_16x16x32_bf16 v[160:163], v[90:93], v[164:167], v[160:163]
	v_mfma_f32_16x16x32_bf16 v[156:159], v[100:103], v[164:167], v[156:159]
	v_mfma_f32_16x16x32_bf16 v[144:147], v[90:93], v[172:175], v[144:147]
	v_mfma_f32_16x16x32_bf16 v[140:143], v[100:103], v[172:175], v[140:143]
	v_mfma_f32_16x16x32_bf16 v[124:127], v[90:93], v[180:183], v[124:127]
	v_mfma_f32_16x16x32_bf16 v[116:119], v[100:103], v[180:183], v[116:119]
	v_mfma_f32_16x16x32_bf16 v[78:81], v[90:93], v[188:191], v[78:81]
	v_mfma_f32_16x16x32_bf16 v[74:77], v[100:103], v[188:191], v[74:77]
	v_mfma_f32_16x16x32_bf16 v[160:163], v[94:97], v[168:171], v[160:163]
	v_mfma_f32_16x16x32_bf16 v[156:159], v[104:107], v[168:171], v[156:159]
	v_mfma_f32_16x16x32_bf16 v[144:147], v[94:97], v[176:179], v[144:147]
	v_mfma_f32_16x16x32_bf16 v[140:143], v[104:107], v[176:179], v[140:143]
	v_mfma_f32_16x16x32_bf16 v[124:127], v[94:97], v[184:187], v[124:127]
	v_mfma_f32_16x16x32_bf16 v[116:119], v[104:107], v[184:187], v[116:119]
	v_mfma_f32_16x16x32_bf16 v[78:81], v[94:97], v[192:195], v[78:81]
	v_mfma_f32_16x16x32_bf16 v[74:77], v[104:107], v[192:195], v[74:77]
	s_setprio 0
	s_setprio 1
	v_mfma_f32_16x16x32_bf16 v[152:155], v[108:111], v[164:167], v[152:155]
	v_mfma_f32_16x16x32_bf16 v[148:151], v[120:123], v[164:167], v[148:151]
	v_mfma_f32_16x16x32_bf16 v[136:139], v[108:111], v[172:175], v[136:139]
	v_mfma_f32_16x16x32_bf16 v[132:135], v[120:123], v[172:175], v[132:135]
	v_mfma_f32_16x16x32_bf16 v[86:89], v[108:111], v[180:183], v[86:89]
	v_mfma_f32_16x16x32_bf16 v[82:85], v[120:123], v[180:183], v[82:85]
	v_mfma_f32_16x16x32_bf16 v[70:73], v[108:111], v[188:191], v[70:73]
	v_mfma_f32_16x16x32_bf16 v[66:69], v[120:123], v[188:191], v[66:69]
	v_mfma_f32_16x16x32_bf16 v[152:155], v[112:115], v[168:171], v[152:155]
	v_mfma_f32_16x16x32_bf16 v[148:151], v[128:131], v[168:171], v[148:151]
	v_mfma_f32_16x16x32_bf16 v[136:139], v[112:115], v[176:179], v[136:139]
	v_mfma_f32_16x16x32_bf16 v[132:135], v[128:131], v[176:179], v[132:135]
	v_mfma_f32_16x16x32_bf16 v[86:89], v[112:115], v[184:187], v[86:89]
	v_mfma_f32_16x16x32_bf16 v[82:85], v[128:131], v[184:187], v[82:85]
	v_mfma_f32_16x16x32_bf16 v[70:73], v[112:115], v[192:195], v[70:73]
	v_mfma_f32_16x16x32_bf16 v[66:69], v[128:131], v[192:195], v[66:69]
	s_setprio 0
	s_barrier
	s_add_i32 s4, s6, s91
	v_lshl_add_u64 v[200:201], v[200:201], 0, s[42:43]
	s_mov_b32 m0, s4
	ds_read_b128 v[164:167], v241 offset:49152
	ds_read_b128 v[168:171], v241 offset:50176
	ds_read_b128 v[172:175], v241 offset:51200
	ds_read_b128 v[176:179], v241 offset:52224
	ds_read_b128 v[180:183], v241 offset:53248
	ds_read_b128 v[184:187], v241 offset:54272
	ds_read_b128 v[188:191], v241 offset:55296
	ds_read_b128 v[192:195], v241 offset:56320
	global_load_lds_dwordx4 v[200:201], off
	s_add_i32 m0, s4, 0x2000
	s_add_u32 s4, s70, 0x40080
	v_lshl_add_u64 v[200:201], v[202:203], 0, s[42:43]
	s_addc_u32 s5, s71, 0
	s_add_i32 s6, s7, s91
	global_load_lds_dwordx4 v[200:201], off
	v_lshl_add_u64 v[200:201], s[4:5], 0, v[204:205]
	s_mov_b32 m0, s6
	s_nop 0
	global_load_lds_dwordx4 v[200:201], off
	v_lshl_add_u64 v[200:201], s[4:5], 0, v[208:209]
	s_add_i32 m0, s6, 0x2000
	s_nop 0
	global_load_lds_dwordx4 v[200:201], off
	v_lshl_add_u64 v[200:201], v[210:211], 0, s[42:43]
	s_add_i32 m0, s44, 0x8000
	s_nop 0
	global_load_lds_dwordx4 v[200:201], off
	v_lshl_add_u64 v[200:201], v[212:213], 0, s[42:43]
	s_add_i32 m0, s44, 0xa000
	s_nop 0
	global_load_lds_dwordx4 v[200:201], off
	s_waitcnt vmcnt(8)
	s_waitcnt lgkmcnt(0)
	s_setprio 1
	s_barrier
	v_mfma_f32_16x16x32_bf16 v[62:65], v[90:93], v[164:167], v[62:65]
	v_mfma_f32_16x16x32_bf16 v[58:61], v[100:103], v[164:167], v[58:61]
	v_mfma_f32_16x16x32_bf16 v[46:49], v[90:93], v[172:175], v[46:49]
	v_mfma_f32_16x16x32_bf16 v[42:45], v[100:103], v[172:175], v[42:45]
	v_mfma_f32_16x16x32_bf16 v[30:33], v[90:93], v[180:183], v[30:33]
	v_mfma_f32_16x16x32_bf16 v[26:29], v[100:103], v[180:183], v[26:29]
	v_mfma_f32_16x16x32_bf16 v[14:17], v[90:93], v[188:191], v[14:17]
	v_mfma_f32_16x16x32_bf16 v[10:13], v[100:103], v[188:191], v[10:13]
	v_mfma_f32_16x16x32_bf16 v[62:65], v[94:97], v[168:171], v[62:65]
	v_mfma_f32_16x16x32_bf16 v[58:61], v[104:107], v[168:171], v[58:61]
	v_mfma_f32_16x16x32_bf16 v[46:49], v[94:97], v[176:179], v[46:49]
	v_mfma_f32_16x16x32_bf16 v[42:45], v[104:107], v[176:179], v[42:45]
	v_mfma_f32_16x16x32_bf16 v[30:33], v[94:97], v[184:187], v[30:33]
	v_mfma_f32_16x16x32_bf16 v[26:29], v[104:107], v[184:187], v[26:29]
	v_mfma_f32_16x16x32_bf16 v[14:17], v[94:97], v[192:195], v[14:17]
	v_mfma_f32_16x16x32_bf16 v[10:13], v[104:107], v[192:195], v[10:13]
	s_setprio 0
	s_setprio 1
	v_mfma_f32_16x16x32_bf16 v[54:57], v[108:111], v[164:167], v[54:57]
	v_mfma_f32_16x16x32_bf16 v[50:53], v[120:123], v[164:167], v[50:53]
	v_mfma_f32_16x16x32_bf16 v[38:41], v[108:111], v[172:175], v[38:41]
	v_mfma_f32_16x16x32_bf16 v[34:37], v[120:123], v[172:175], v[34:37]
	v_mfma_f32_16x16x32_bf16 v[22:25], v[108:111], v[180:183], v[22:25]
	v_mfma_f32_16x16x32_bf16 v[18:21], v[120:123], v[180:183], v[18:21]
	v_mfma_f32_16x16x32_bf16 v[6:9], v[108:111], v[188:191], v[6:9]
	v_mfma_f32_16x16x32_bf16 v[2:5], v[120:123], v[188:191], v[2:5]
	v_mfma_f32_16x16x32_bf16 v[54:57], v[112:115], v[168:171], v[54:57]
	v_mfma_f32_16x16x32_bf16 v[50:53], v[128:131], v[168:171], v[50:53]
	v_mfma_f32_16x16x32_bf16 v[38:41], v[112:115], v[176:179], v[38:41]
	v_mfma_f32_16x16x32_bf16 v[34:37], v[128:131], v[176:179], v[34:37]
	v_mfma_f32_16x16x32_bf16 v[22:25], v[112:115], v[184:187], v[22:25]
	v_mfma_f32_16x16x32_bf16 v[18:21], v[128:131], v[184:187], v[18:21]
	v_mfma_f32_16x16x32_bf16 v[6:9], v[112:115], v[192:195], v[6:9]
	v_mfma_f32_16x16x32_bf16 v[2:5], v[128:131], v[192:195], v[2:5]
	s_setprio 0
	s_barrier
	s_mov_b32 s100, 0
	s_add_i32 s97, s97, 2
	s_add_u32 s68, s68, 0x100
	s_addc_u32 s69, s69, 0
	s_add_u32 vcc_hi, vcc_hi, 0x100
	s_addc_u32 s96, s96, 0
	s_cmp_gt_u32 s97, 13
	s_cbranch_scc0 .LBB0_864
	s_mov_b32 s100, 1
	s_and_b64 vcc, exec, s[12:13]
	s_cbranch_vccz .LBB0_867
	s_nop 0

.LBB0_883:
	s_or_b64 exec, exec, s[70:71]
	s_andn2_b64 vcc, exec, s[40:41]
	s_mov_b64 s[40:41], -1
	s_cbranch_vccnz .LBB0_856
	s_andn2_b64 vcc, exec, s[14:15]
	s_cbranch_vccnz .LBB0_855
	s_nop 0
	s_branch .LBB0_855

.LBB0_886:
	s_waitcnt vmcnt(0)
	v_readlane_b32 s70, v255, 37
	v_readlane_b32 s71, v255, 38
	s_mov_b64 s[92:93], s[10:11]
	s_and_b64 vcc, exec, s[12:13]
	s_cbranch_vccz .Lmy_ua_g2a
	s_barrier

.Lmy_sk6:
	s_waitcnt lgkmcnt(0)
	s_setprio 1
	s_barrier
	v_mfma_f32_16x16x32_bf16 v[62:65], v[86:89], v[164:167], v[62:65]
	v_mfma_f32_16x16x32_bf16 v[58:61], v[100:103], v[164:167], v[58:61]
	v_mfma_f32_16x16x32_bf16 v[46:49], v[86:89], v[172:175], v[46:49]
	v_mfma_f32_16x16x32_bf16 v[42:45], v[100:103], v[172:175], v[42:45]
	v_mfma_f32_16x16x32_bf16 v[30:33], v[86:89], v[180:183], v[30:33]
	v_mfma_f32_16x16x32_bf16 v[26:29], v[100:103], v[180:183], v[26:29]
	v_mfma_f32_16x16x32_bf16 v[14:17], v[86:89], v[188:191], v[14:17]
	v_mfma_f32_16x16x32_bf16 v[10:13], v[100:103], v[188:191], v[10:13]
	v_mfma_f32_16x16x32_bf16 v[62:65], v[90:93], v[168:171], v[62:65]
	v_mfma_f32_16x16x32_bf16 v[58:61], v[104:107], v[168:171], v[58:61]
	v_mfma_f32_16x16x32_bf16 v[46:49], v[90:93], v[176:179], v[46:49]
	v_mfma_f32_16x16x32_bf16 v[42:45], v[104:107], v[176:179], v[42:45]
	v_mfma_f32_16x16x32_bf16 v[30:33], v[90:93], v[184:187], v[30:33]
	v_mfma_f32_16x16x32_bf16 v[26:29], v[104:107], v[184:187], v[26:29]
	v_mfma_f32_16x16x32_bf16 v[14:17], v[90:93], v[192:195], v[14:17]
	v_mfma_f32_16x16x32_bf16 v[10:13], v[104:107], v[192:195], v[10:13]
	s_setprio 0
	s_setprio 1
	v_mfma_f32_16x16x32_bf16 v[54:57], v[108:111], v[164:167], v[54:57]
	v_mfma_f32_16x16x32_bf16 v[50:53], v[116:119], v[164:167], v[50:53]
	v_mfma_f32_16x16x32_bf16 v[38:41], v[108:111], v[172:175], v[38:41]
	v_mfma_f32_16x16x32_bf16 v[34:37], v[116:119], v[172:175], v[34:37]
	v_mfma_f32_16x16x32_bf16 v[22:25], v[108:111], v[180:183], v[22:25]
	v_mfma_f32_16x16x32_bf16 v[18:21], v[116:119], v[180:183], v[18:21]
	v_mfma_f32_16x16x32_bf16 v[6:9], v[108:111], v[188:191], v[6:9]
	v_mfma_f32_16x16x32_bf16 v[2:5], v[116:119], v[188:191], v[2:5]
	v_mfma_f32_16x16x32_bf16 v[54:57], v[112:115], v[168:171], v[54:57]
	v_mfma_f32_16x16x32_bf16 v[50:53], v[124:127], v[168:171], v[50:53]
	v_mfma_f32_16x16x32_bf16 v[38:41], v[112:115], v[176:179], v[38:41]
	v_mfma_f32_16x16x32_bf16 v[34:37], v[124:127], v[176:179], v[34:37]
	v_mfma_f32_16x16x32_bf16 v[22:25], v[112:115], v[184:187], v[22:25]
	v_mfma_f32_16x16x32_bf16 v[18:21], v[124:127], v[184:187], v[18:21]
	v_mfma_f32_16x16x32_bf16 v[6:9], v[112:115], v[192:195], v[6:9]
	v_mfma_f32_16x16x32_bf16 v[2:5], v[124:127], v[192:195], v[2:5]
	s_setprio 0
	s_barrier
	s_add_i32 s45, 0, 0x18000
	s_add_i32 s97, 0, 0x1c000
	v_add_u32_e32 v104, s45, v223
	v_add_u32_e32 v124, s97, v223
	ds_read_b128 v[86:89], v104
	ds_read_b128 v[90:93], v104 offset:1024
	ds_read_b128 v[100:103], v104 offset:2048
	ds_read_b128 v[104:107], v104 offset:3072
	ds_read_b128 v[108:111], v124
	ds_read_b128 v[112:115], v124 offset:1024
	ds_read_b128 v[116:119], v124 offset:2048
	ds_read_b128 v[124:127], v124 offset:3072
	s_add_u32 s4, s70, 0x40000
	s_addc_u32 s5, s71, 0
	v_lshl_add_u64 v[214:215], s[4:5], 0, v[98:99]
	s_add_i32 m0, s44, 0x4000
	ds_read_b128 v[164:167], v225 offset:32768
	ds_read_b128 v[168:171], v225 offset:33792
	ds_read_b128 v[172:175], v225 offset:34816
	ds_read_b128 v[176:179], v225 offset:35840
	ds_read_b128 v[180:183], v225 offset:36864
	ds_read_b128 v[184:187], v225 offset:37888
	ds_read_b128 v[188:191], v225 offset:38912
	ds_read_b128 v[192:195], v225 offset:39936
	global_load_lds_dwordx4 v[214:215], off
	v_lshl_add_u64 v[214:215], s[4:5], 0, v[206:207]
	s_add_i32 m0, s44, 0x6000
	s_nop 0
	global_load_lds_dwordx4 v[214:215], off
	s_waitcnt vmcnt(8)
	s_waitcnt lgkmcnt(0)
	s_setprio 1
	s_barrier
	v_mfma_f32_16x16x32_bf16 v[160:163], v[86:89], v[164:167], v[160:163]
	v_mfma_f32_16x16x32_bf16 v[156:159], v[100:103], v[164:167], v[156:159]
	v_mfma_f32_16x16x32_bf16 v[144:147], v[86:89], v[172:175], v[144:147]
	v_mfma_f32_16x16x32_bf16 v[140:143], v[100:103], v[172:175], v[140:143]
	v_mfma_f32_16x16x32_bf16 v[128:131], v[86:89], v[180:183], v[128:131]
	v_mfma_f32_16x16x32_bf16 v[120:123], v[100:103], v[180:183], v[120:123]
	v_mfma_f32_16x16x32_bf16 v[78:81], v[86:89], v[188:191], v[78:81]
	v_mfma_f32_16x16x32_bf16 v[74:77], v[100:103], v[188:191], v[74:77]
	v_mfma_f32_16x16x32_bf16 v[160:163], v[90:93], v[168:171], v[160:163]
	v_mfma_f32_16x16x32_bf16 v[156:159], v[104:107], v[168:171], v[156:159]
	v_mfma_f32_16x16x32_bf16 v[144:147], v[90:93], v[176:179], v[144:147]
	v_mfma_f32_16x16x32_bf16 v[140:143], v[104:107], v[176:179], v[140:143]
	v_mfma_f32_16x16x32_bf16 v[128:131], v[90:93], v[184:187], v[128:131]
	v_mfma_f32_16x16x32_bf16 v[120:123], v[104:107], v[184:187], v[120:123]
	v_mfma_f32_16x16x32_bf16 v[78:81], v[90:93], v[192:195], v[78:81]
	v_mfma_f32_16x16x32_bf16 v[74:77], v[104:107], v[192:195], v[74:77]
	s_setprio 0
	s_setprio 1
	v_mfma_f32_16x16x32_bf16 v[152:155], v[108:111], v[164:167], v[152:155]
	v_mfma_f32_16x16x32_bf16 v[148:151], v[116:119], v[164:167], v[148:151]
	v_mfma_f32_16x16x32_bf16 v[136:139], v[108:111], v[172:175], v[136:139]
	v_mfma_f32_16x16x32_bf16 v[132:135], v[116:119], v[172:175], v[132:135]
	v_mfma_f32_16x16x32_bf16 v[94:97], v[108:111], v[180:183], v[94:97]
	v_mfma_f32_16x16x32_bf16 v[82:85], v[116:119], v[180:183], v[82:85]
	v_mfma_f32_16x16x32_bf16 v[70:73], v[108:111], v[188:191], v[70:73]
	v_mfma_f32_16x16x32_bf16 v[66:69], v[116:119], v[188:191], v[66:69]
	v_mfma_f32_16x16x32_bf16 v[152:155], v[112:115], v[168:171], v[152:155]
	v_mfma_f32_16x16x32_bf16 v[148:151], v[124:127], v[168:171], v[148:151]
	v_mfma_f32_16x16x32_bf16 v[136:139], v[112:115], v[176:179], v[136:139]
	v_mfma_f32_16x16x32_bf16 v[132:135], v[124:127], v[176:179], v[132:135]
	v_mfma_f32_16x16x32_bf16 v[94:97], v[112:115], v[184:187], v[94:97]
	v_mfma_f32_16x16x32_bf16 v[82:85], v[124:127], v[184:187], v[82:85]
	v_mfma_f32_16x16x32_bf16 v[70:73], v[112:115], v[192:195], v[70:73]
	v_mfma_f32_16x16x32_bf16 v[66:69], v[124:127], v[192:195], v[66:69]
	s_setprio 0
	s_barrier
	s_add_i32 s4, s45, s74
	v_lshl_add_u64 v[200:201], v[200:201], 0, s[42:43]
	s_mov_b32 m0, s4
	ds_read_b128 v[164:167], v225 offset:49152
	ds_read_b128 v[168:171], v225 offset:50176
	ds_read_b128 v[172:175], v225 offset:51200
	ds_read_b128 v[176:179], v225 offset:52224
	ds_read_b128 v[180:183], v225 offset:53248
	ds_read_b128 v[184:187], v225 offset:54272
	ds_read_b128 v[188:191], v225 offset:55296
	ds_read_b128 v[192:195], v225 offset:56320
	global_load_lds_dwordx4 v[200:201], off
	s_add_i32 m0, s4, 0x2000
	s_add_u32 s4, s68, 0x40080
	v_lshl_add_u64 v[200:201], v[202:203], 0, s[42:43]
	s_addc_u32 s5, s69, 0
	s_add_i32 s45, s97, s74
	global_load_lds_dwordx4 v[200:201], off
	v_lshl_add_u64 v[200:201], s[4:5], 0, v[204:205]
	s_mov_b32 m0, s45
	s_nop 0
	global_load_lds_dwordx4 v[200:201], off
	v_lshl_add_u64 v[200:201], s[4:5], 0, v[208:209]
	s_add_i32 m0, s45, 0x2000
	s_nop 0
	global_load_lds_dwordx4 v[200:201], off
	v_lshl_add_u64 v[200:201], v[210:211], 0, s[42:43]
	s_add_i32 m0, s44, 0x8000
	s_nop 0
	global_load_lds_dwordx4 v[200:201], off
	v_lshl_add_u64 v[200:201], v[212:213], 0, s[42:43]
	s_add_i32 m0, s44, 0xa000
	s_nop 0
	global_load_lds_dwordx4 v[200:201], off
	s_waitcnt vmcnt(8)
	s_waitcnt lgkmcnt(0)
	s_setprio 1
	s_barrier
	v_mfma_f32_16x16x32_bf16 v[62:65], v[86:89], v[164:167], v[62:65]
	v_mfma_f32_16x16x32_bf16 v[58:61], v[100:103], v[164:167], v[58:61]
	v_mfma_f32_16x16x32_bf16 v[46:49], v[86:89], v[172:175], v[46:49]
	v_mfma_f32_16x16x32_bf16 v[42:45], v[100:103], v[172:175], v[42:45]
	v_mfma_f32_16x16x32_bf16 v[30:33], v[86:89], v[180:183], v[30:33]
	v_mfma_f32_16x16x32_bf16 v[26:29], v[100:103], v[180:183], v[26:29]
	v_mfma_f32_16x16x32_bf16 v[14:17], v[86:89], v[188:191], v[14:17]
	v_mfma_f32_16x16x32_bf16 v[10:13], v[100:103], v[188:191], v[10:13]
	v_mfma_f32_16x16x32_bf16 v[62:65], v[90:93], v[168:171], v[62:65]
	v_mfma_f32_16x16x32_bf16 v[58:61], v[104:107], v[168:171], v[58:61]
	v_mfma_f32_16x16x32_bf16 v[46:49], v[90:93], v[176:179], v[46:49]
	v_mfma_f32_16x16x32_bf16 v[42:45], v[104:107], v[176:179], v[42:45]
	v_mfma_f32_16x16x32_bf16 v[30:33], v[90:93], v[184:187], v[30:33]
	v_mfma_f32_16x16x32_bf16 v[26:29], v[104:107], v[184:187], v[26:29]
	v_mfma_f32_16x16x32_bf16 v[14:17], v[90:93], v[192:195], v[14:17]
	v_mfma_f32_16x16x32_bf16 v[10:13], v[104:107], v[192:195], v[10:13]
	s_setprio 0
	s_setprio 1
	v_mfma_f32_16x16x32_bf16 v[54:57], v[108:111], v[164:167], v[54:57]
	v_mfma_f32_16x16x32_bf16 v[50:53], v[116:119], v[164:167], v[50:53]
	v_mfma_f32_16x16x32_bf16 v[38:41], v[108:111], v[172:175], v[38:41]
	v_mfma_f32_16x16x32_bf16 v[34:37], v[116:119], v[172:175], v[34:37]
	v_mfma_f32_16x16x32_bf16 v[22:25], v[108:111], v[180:183], v[22:25]
	v_mfma_f32_16x16x32_bf16 v[18:21], v[116:119], v[180:183], v[18:21]
	v_mfma_f32_16x16x32_bf16 v[6:9], v[108:111], v[188:191], v[6:9]
	v_mfma_f32_16x16x32_bf16 v[2:5], v[116:119], v[188:191], v[2:5]
	v_mfma_f32_16x16x32_bf16 v[54:57], v[112:115], v[168:171], v[54:57]
	v_mfma_f32_16x16x32_bf16 v[50:53], v[124:127], v[168:171], v[50:53]
	v_mfma_f32_16x16x32_bf16 v[38:41], v[112:115], v[176:179], v[38:41]
	v_mfma_f32_16x16x32_bf16 v[34:37], v[124:127], v[176:179], v[34:37]
	v_mfma_f32_16x16x32_bf16 v[22:25], v[112:115], v[184:187], v[22:25]
	v_mfma_f32_16x16x32_bf16 v[18:21], v[124:127], v[184:187], v[18:21]
	v_mfma_f32_16x16x32_bf16 v[6:9], v[112:115], v[192:195], v[6:9]
	v_mfma_f32_16x16x32_bf16 v[2:5], v[124:127], v[192:195], v[2:5]
	s_setprio 0
	s_barrier
	s_mov_b32 s100, 0
	s_add_i32 s96, s96, 2
	s_add_u32 s56, s56, 0x100
	s_addc_u32 s57, s57, 0
	s_add_u32 s95, s95, 0x100
	s_addc_u32 vcc_lo, vcc_lo, 0
	s_cmp_gt_u32 s96, 13
	s_cbranch_scc0 .LBB0_908
	s_mov_b32 s100, 1
	v_mov_b32_e32 v196, 0x2d00
	v_mov_b32_e32 v231, 0x2400
	v_mov_b32_e32 v228, 0x1b00
	s_and_b64 vcc, exec, s[0:1]
	s_movk_i32 s21, 0x4000
	s_cbranch_vccz .LBB0_911
	s_nop 0

.LBB0_927:
	s_or_b64 exec, exec, s[68:69]
	s_andn2_b64 vcc, exec, s[38:39]
	s_mov_b64 s[38:39], -1
	s_cbranch_vccnz .LBB0_900
	v_readlane_b32 s4, v255, 44
	v_readlane_b32 s5, v255, 45
	s_andn2_b64 vcc, exec, s[4:5]
	s_cbranch_vccnz .LBB0_899
	s_nop 0
	s_branch .LBB0_899

.LBB0_930:
	s_waitcnt vmcnt(0)
	v_readlane_b32 s52, v252, 36
	v_readlane_b32 s8, v255, 31
	v_readlane_b32 s74, v255, 33
	v_readlane_b32 s16, v255, 42
	v_readlane_b32 s53, v252, 37
	v_readlane_b32 s9, v255, 32
	v_readlane_b32 s75, v255, 34
	v_readlane_b32 s17, v255, 43
	s_and_b64 vcc, exec, s[0:1]
	s_cbranch_vccz .Lmy_ua_g2b
	s_barrier

.Lmy_sk8:
	s_waitcnt lgkmcnt(0)
	s_setprio 1
	s_barrier
	v_mfma_f32_16x16x32_bf16 v[62:65], v[132:135], v[204:207], v[62:65]
	v_mfma_f32_16x16x32_bf16 v[58:61], v[140:143], v[204:207], v[58:61]
	v_mfma_f32_16x16x32_bf16 v[46:49], v[132:135], v[212:215], v[46:49]
	v_mfma_f32_16x16x32_bf16 v[42:45], v[140:143], v[212:215], v[42:45]
	v_mfma_f32_16x16x32_bf16 v[30:33], v[132:135], v[220:223], v[30:33]
	v_mfma_f32_16x16x32_bf16 v[26:29], v[140:143], v[220:223], v[26:29]
	v_mfma_f32_16x16x32_bf16 v[14:17], v[132:135], v[238:241], v[14:17]
	v_mfma_f32_16x16x32_bf16 v[10:13], v[140:143], v[238:241], v[10:13]
	v_mfma_f32_16x16x32_bf16 v[62:65], v[136:139], v[208:211], v[62:65]
	v_mfma_f32_16x16x32_bf16 v[58:61], v[144:147], v[208:211], v[58:61]
	v_mfma_f32_16x16x32_bf16 v[46:49], v[136:139], v[216:219], v[46:49]
	v_mfma_f32_16x16x32_bf16 v[42:45], v[144:147], v[216:219], v[42:45]
	v_mfma_f32_16x16x32_bf16 v[30:33], v[136:139], v[224:227], v[30:33]
	v_mfma_f32_16x16x32_bf16 v[26:29], v[144:147], v[224:227], v[26:29]
	v_mfma_f32_16x16x32_bf16 v[14:17], v[136:139], v[242:245], v[14:17]
	v_mfma_f32_16x16x32_bf16 v[10:13], v[144:147], v[242:245], v[10:13]
	s_setprio 0
	s_setprio 1
	v_mfma_f32_16x16x32_bf16 v[54:57], v[156:159], v[204:207], v[54:57]
	v_mfma_f32_16x16x32_bf16 v[50:53], v[192:195], v[204:207], v[50:53]
	v_mfma_f32_16x16x32_bf16 v[38:41], v[156:159], v[212:215], v[38:41]
	v_mfma_f32_16x16x32_bf16 v[34:37], v[192:195], v[212:215], v[34:37]
	v_mfma_f32_16x16x32_bf16 v[22:25], v[156:159], v[220:223], v[22:25]
	v_mfma_f32_16x16x32_bf16 v[18:21], v[192:195], v[220:223], v[18:21]
	v_mfma_f32_16x16x32_bf16 v[6:9], v[156:159], v[238:241], v[6:9]
	v_mfma_f32_16x16x32_bf16 v[2:5], v[192:195], v[238:241], v[2:5]
	v_mfma_f32_16x16x32_bf16 v[54:57], v[162:165], v[208:211], v[54:57]
	v_mfma_f32_16x16x32_bf16 v[50:53], v[200:203], v[208:211], v[50:53]
	v_mfma_f32_16x16x32_bf16 v[38:41], v[162:165], v[216:219], v[38:41]
	v_mfma_f32_16x16x32_bf16 v[34:37], v[200:203], v[216:219], v[34:37]
	v_mfma_f32_16x16x32_bf16 v[22:25], v[162:165], v[224:227], v[22:25]
	v_mfma_f32_16x16x32_bf16 v[18:21], v[200:203], v[224:227], v[18:21]
	v_mfma_f32_16x16x32_bf16 v[6:9], v[162:165], v[242:245], v[6:9]
	v_mfma_f32_16x16x32_bf16 v[2:5], v[200:203], v[242:245], v[2:5]
	s_setprio 0
	s_barrier
	s_add_i32 s6, 0, 0x18000
	s_add_i32 s7, 0, 0x1c000
	v_add_u32_e32 v144, s6, v189
	v_add_u32_e32 v160, s7, v189
	ds_read_b128 v[132:135], v144
	ds_read_b128 v[136:139], v144 offset:1024
	ds_read_b128 v[140:143], v144 offset:2048
	ds_read_b128 v[144:147], v144 offset:3072
	ds_read_b128 v[156:159], v160
	ds_read_b128 v[162:165], v160 offset:1024
	ds_read_b128 v[192:195], v160 offset:2048
	ds_read_b128 v[200:203], v160 offset:3072
	s_add_u32 s4, s68, 0x40000
	s_addc_u32 s5, s69, 0
	v_lshl_add_u64 v[246:247], s[4:5], 0, v[98:99]
	s_add_i32 m0, s44, 0x4000
	ds_read_b128 v[204:207], v191 offset:32768
	ds_read_b128 v[208:211], v191 offset:33792
	ds_read_b128 v[212:215], v191 offset:34816
	ds_read_b128 v[216:219], v191 offset:35840
	ds_read_b128 v[220:223], v191 offset:36864
	ds_read_b128 v[224:227], v191 offset:37888
	ds_read_b128 v[238:241], v191 offset:38912
	ds_read_b128 v[242:245], v191 offset:39936
	global_load_lds_dwordx4 v[246:247], off
	v_lshl_add_u64 v[246:247], s[4:5], 0, v[150:151]
	s_add_i32 m0, s44, 0x6000
	s_nop 0
	global_load_lds_dwordx4 v[246:247], off
	s_waitcnt vmcnt(8)
	s_waitcnt lgkmcnt(0)
	s_setprio 1
	s_barrier
	v_mfma_f32_16x16x32_bf16 v[128:131], v[132:135], v[204:207], v[128:131]
	v_mfma_f32_16x16x32_bf16 v[124:127], v[140:143], v[204:207], v[124:127]
	v_mfma_f32_16x16x32_bf16 v[112:115], v[132:135], v[212:215], v[112:115]
	v_mfma_f32_16x16x32_bf16 v[108:111], v[140:143], v[212:215], v[108:111]
	v_mfma_f32_16x16x32_bf16 v[94:97], v[132:135], v[220:223], v[94:97]
	v_mfma_f32_16x16x32_bf16 v[90:93], v[140:143], v[220:223], v[90:93]
	v_mfma_f32_16x16x32_bf16 v[78:81], v[132:135], v[238:241], v[78:81]
	v_mfma_f32_16x16x32_bf16 v[74:77], v[140:143], v[238:241], v[74:77]
	v_mfma_f32_16x16x32_bf16 v[128:131], v[136:139], v[208:211], v[128:131]
	v_mfma_f32_16x16x32_bf16 v[124:127], v[144:147], v[208:211], v[124:127]
	v_mfma_f32_16x16x32_bf16 v[112:115], v[136:139], v[216:219], v[112:115]
	v_mfma_f32_16x16x32_bf16 v[108:111], v[144:147], v[216:219], v[108:111]
	v_mfma_f32_16x16x32_bf16 v[94:97], v[136:139], v[224:227], v[94:97]
	v_mfma_f32_16x16x32_bf16 v[90:93], v[144:147], v[224:227], v[90:93]
	v_mfma_f32_16x16x32_bf16 v[78:81], v[136:139], v[242:245], v[78:81]
	v_mfma_f32_16x16x32_bf16 v[74:77], v[144:147], v[242:245], v[74:77]
	s_setprio 0
	s_setprio 1
	v_mfma_f32_16x16x32_bf16 v[120:123], v[156:159], v[204:207], v[120:123]
	v_mfma_f32_16x16x32_bf16 v[116:119], v[192:195], v[204:207], v[116:119]
	v_mfma_f32_16x16x32_bf16 v[104:107], v[156:159], v[212:215], v[104:107]
	v_mfma_f32_16x16x32_bf16 v[100:103], v[192:195], v[212:215], v[100:103]
	v_mfma_f32_16x16x32_bf16 v[86:89], v[156:159], v[220:223], v[86:89]
	v_mfma_f32_16x16x32_bf16 v[82:85], v[192:195], v[220:223], v[82:85]
	v_mfma_f32_16x16x32_bf16 v[70:73], v[156:159], v[238:241], v[70:73]
	v_mfma_f32_16x16x32_bf16 v[66:69], v[192:195], v[238:241], v[66:69]
	v_mfma_f32_16x16x32_bf16 v[120:123], v[162:165], v[208:211], v[120:123]
	v_mfma_f32_16x16x32_bf16 v[116:119], v[200:203], v[208:211], v[116:119]
	v_mfma_f32_16x16x32_bf16 v[104:107], v[162:165], v[216:219], v[104:107]
	v_mfma_f32_16x16x32_bf16 v[100:103], v[200:203], v[216:219], v[100:103]
	v_mfma_f32_16x16x32_bf16 v[86:89], v[162:165], v[224:227], v[86:89]
	v_mfma_f32_16x16x32_bf16 v[82:85], v[200:203], v[224:227], v[82:85]
	v_mfma_f32_16x16x32_bf16 v[70:73], v[162:165], v[242:245], v[70:73]
	v_mfma_f32_16x16x32_bf16 v[66:69], v[200:203], v[242:245], v[66:69]
	s_setprio 0
	s_barrier
	s_add_i32 s4, s6, s70
	v_lshl_add_u64 v[166:167], v[166:167], 0, s[42:43]
	s_mov_b32 m0, s4
	ds_read_b128 v[204:207], v191 offset:49152
	ds_read_b128 v[208:211], v191 offset:50176
	ds_read_b128 v[212:215], v191 offset:51200
	ds_read_b128 v[216:219], v191 offset:52224
	ds_read_b128 v[220:223], v191 offset:53248
	ds_read_b128 v[224:227], v191 offset:54272
	ds_read_b128 v[238:241], v191 offset:55296
	ds_read_b128 v[242:245], v191 offset:56320
	global_load_lds_dwordx4 v[166:167], off
	s_add_i32 m0, s4, 0x2000
	s_add_u32 s4, s56, 0x40080
	v_lshl_add_u64 v[166:167], v[170:171], 0, s[42:43]
	s_addc_u32 s5, s57, 0
	s_add_i32 s6, s7, s70
	global_load_lds_dwordx4 v[166:167], off
	v_lshl_add_u64 v[166:167], s[4:5], 0, v[148:149]
	s_mov_b32 m0, s6
	s_nop 0
	global_load_lds_dwordx4 v[166:167], off
	v_lshl_add_u64 v[166:167], s[4:5], 0, v[152:153]
	s_add_i32 m0, s6, 0x2000
	s_nop 0
	global_load_lds_dwordx4 v[166:167], off
	v_lshl_add_u64 v[166:167], v[176:177], 0, s[42:43]
	s_add_i32 m0, s44, 0x8000
	s_nop 0
	global_load_lds_dwordx4 v[166:167], off
	v_lshl_add_u64 v[166:167], v[180:181], 0, s[42:43]
	s_add_i32 m0, s44, 0xa000
	s_nop 0
	global_load_lds_dwordx4 v[166:167], off
	s_waitcnt vmcnt(8)
	s_waitcnt lgkmcnt(0)
	s_setprio 1
	s_barrier
	v_mfma_f32_16x16x32_bf16 v[62:65], v[132:135], v[204:207], v[62:65]
	v_mfma_f32_16x16x32_bf16 v[58:61], v[140:143], v[204:207], v[58:61]
	v_mfma_f32_16x16x32_bf16 v[46:49], v[132:135], v[212:215], v[46:49]
	v_mfma_f32_16x16x32_bf16 v[42:45], v[140:143], v[212:215], v[42:45]
	v_mfma_f32_16x16x32_bf16 v[30:33], v[132:135], v[220:223], v[30:33]
	v_mfma_f32_16x16x32_bf16 v[26:29], v[140:143], v[220:223], v[26:29]
	v_mfma_f32_16x16x32_bf16 v[14:17], v[132:135], v[238:241], v[14:17]
	v_mfma_f32_16x16x32_bf16 v[10:13], v[140:143], v[238:241], v[10:13]
	v_mfma_f32_16x16x32_bf16 v[62:65], v[136:139], v[208:211], v[62:65]
	v_mfma_f32_16x16x32_bf16 v[58:61], v[144:147], v[208:211], v[58:61]
	v_mfma_f32_16x16x32_bf16 v[46:49], v[136:139], v[216:219], v[46:49]
	v_mfma_f32_16x16x32_bf16 v[42:45], v[144:147], v[216:219], v[42:45]
	v_mfma_f32_16x16x32_bf16 v[30:33], v[136:139], v[224:227], v[30:33]
	v_mfma_f32_16x16x32_bf16 v[26:29], v[144:147], v[224:227], v[26:29]
	v_mfma_f32_16x16x32_bf16 v[14:17], v[136:139], v[242:245], v[14:17]
	v_mfma_f32_16x16x32_bf16 v[10:13], v[144:147], v[242:245], v[10:13]
	s_setprio 0
	s_setprio 1
	v_mfma_f32_16x16x32_bf16 v[54:57], v[156:159], v[204:207], v[54:57]
	v_mfma_f32_16x16x32_bf16 v[50:53], v[192:195], v[204:207], v[50:53]
	v_mfma_f32_16x16x32_bf16 v[38:41], v[156:159], v[212:215], v[38:41]
	v_mfma_f32_16x16x32_bf16 v[34:37], v[192:195], v[212:215], v[34:37]
	v_mfma_f32_16x16x32_bf16 v[22:25], v[156:159], v[220:223], v[22:25]
	v_mfma_f32_16x16x32_bf16 v[18:21], v[192:195], v[220:223], v[18:21]
	v_mfma_f32_16x16x32_bf16 v[6:9], v[156:159], v[238:241], v[6:9]
	v_mfma_f32_16x16x32_bf16 v[2:5], v[192:195], v[238:241], v[2:5]
	v_mfma_f32_16x16x32_bf16 v[54:57], v[162:165], v[208:211], v[54:57]
	v_mfma_f32_16x16x32_bf16 v[50:53], v[200:203], v[208:211], v[50:53]
	v_mfma_f32_16x16x32_bf16 v[38:41], v[162:165], v[216:219], v[38:41]
	v_mfma_f32_16x16x32_bf16 v[34:37], v[200:203], v[216:219], v[34:37]
	v_mfma_f32_16x16x32_bf16 v[22:25], v[162:165], v[224:227], v[22:25]
	v_mfma_f32_16x16x32_bf16 v[18:21], v[200:203], v[224:227], v[18:21]
	v_mfma_f32_16x16x32_bf16 v[6:9], v[162:165], v[242:245], v[6:9]
	v_mfma_f32_16x16x32_bf16 v[2:5], v[200:203], v[242:245], v[2:5]
	s_setprio 0
	s_barrier
	s_mov_b32 s100, 0
	s_add_i32 s92, s92, 2
	s_add_u32 s40, s40, 0x100
	s_addc_u32 s41, s41, 0
	s_add_u32 s90, s90, 0x100
	s_addc_u32 s91, s91, 0
	s_cmp_gt_u32 s92, 13
	s_cbranch_scc0 .LBB0_1011
	s_mov_b32 s100, 1
	s_and_b64 vcc, exec, s[0:1]
	s_cbranch_vccz .LBB0_1014
	s_nop 0

.Lmy_wt_g3_15r:
	s_cbranch_vccnz .LBB0_1003
	s_andn2_b64 vcc, exec, s[10:11]
	s_cbranch_vccnz .LBB0_1002
	s_nop 0
	s_branch .LBB0_1002

.LBB0_1017:
	s_waitcnt vmcnt(0)
	v_readlane_b32 s8, v255, 31
	v_readlane_b32 s74, v255, 33
	v_readlane_b32 s70, v255, 37
	v_readlane_b32 s9, v255, 32
	v_readlane_b32 s75, v255, 34
	v_readlane_b32 s77, v255, 36
	v_readlane_b32 s71, v255, 38
	s_and_b64 vcc, exec, s[0:1]
	s_cbranch_vccz .Lmy_ua_g3
	s_barrier

.Lmy_sk10:
	s_waitcnt lgkmcnt(0)
	s_setprio 1
	s_barrier
	v_mfma_f32_16x16x32_bf16 v[62:65], v[112:115], v[164:167], v[62:65]
	v_mfma_f32_16x16x32_bf16 v[58:61], v[124:127], v[164:167], v[58:61]
	v_mfma_f32_16x16x32_bf16 v[46:49], v[112:115], v[178:181], v[46:49]
	v_mfma_f32_16x16x32_bf16 v[42:45], v[124:127], v[178:181], v[42:45]
	v_mfma_f32_16x16x32_bf16 v[30:33], v[112:115], v[186:189], v[30:33]
	v_mfma_f32_16x16x32_bf16 v[26:29], v[124:127], v[186:189], v[26:29]
	v_mfma_f32_16x16x32_bf16 v[14:17], v[112:115], v[200:203], v[14:17]
	v_mfma_f32_16x16x32_bf16 v[10:13], v[124:127], v[200:203], v[10:13]
	v_mfma_f32_16x16x32_bf16 v[62:65], v[116:119], v[168:171], v[62:65]
	v_mfma_f32_16x16x32_bf16 v[58:61], v[128:131], v[168:171], v[58:61]
	v_mfma_f32_16x16x32_bf16 v[46:49], v[116:119], v[182:185], v[46:49]
	v_mfma_f32_16x16x32_bf16 v[42:45], v[128:131], v[182:185], v[42:45]
	v_mfma_f32_16x16x32_bf16 v[30:33], v[116:119], v[190:193], v[30:33]
	v_mfma_f32_16x16x32_bf16 v[26:29], v[128:131], v[190:193], v[26:29]
	v_mfma_f32_16x16x32_bf16 v[14:17], v[116:119], v[208:211], v[14:17]
	v_mfma_f32_16x16x32_bf16 v[10:13], v[128:131], v[208:211], v[10:13]
	s_setprio 0
	s_setprio 1
	v_mfma_f32_16x16x32_bf16 v[54:57], v[148:151], v[164:167], v[54:57]
	v_mfma_f32_16x16x32_bf16 v[50:53], v[156:159], v[164:167], v[50:53]
	v_mfma_f32_16x16x32_bf16 v[38:41], v[148:151], v[178:181], v[38:41]
	v_mfma_f32_16x16x32_bf16 v[34:37], v[156:159], v[178:181], v[34:37]
	v_mfma_f32_16x16x32_bf16 v[22:25], v[148:151], v[186:189], v[22:25]
	v_mfma_f32_16x16x32_bf16 v[18:21], v[156:159], v[186:189], v[18:21]
	v_mfma_f32_16x16x32_bf16 v[6:9], v[148:151], v[200:203], v[6:9]
	v_mfma_f32_16x16x32_bf16 v[2:5], v[156:159], v[200:203], v[2:5]
	v_mfma_f32_16x16x32_bf16 v[54:57], v[152:155], v[168:171], v[54:57]
	v_mfma_f32_16x16x32_bf16 v[50:53], v[160:163], v[168:171], v[50:53]
	v_mfma_f32_16x16x32_bf16 v[38:41], v[152:155], v[182:185], v[38:41]
	v_mfma_f32_16x16x32_bf16 v[34:37], v[160:163], v[182:185], v[34:37]
	v_mfma_f32_16x16x32_bf16 v[22:25], v[152:155], v[190:193], v[22:25]
	v_mfma_f32_16x16x32_bf16 v[18:21], v[160:163], v[190:193], v[18:21]
	v_mfma_f32_16x16x32_bf16 v[6:9], v[152:155], v[208:211], v[6:9]
	v_mfma_f32_16x16x32_bf16 v[2:5], v[160:163], v[208:211], v[2:5]
	s_setprio 0
	s_barrier
	s_add_i32 s6, 0, 0x18000
	s_add_i32 s7, 0, 0x1c000
	v_add_u32_e32 v128, s6, v205
	v_add_u32_e32 v160, s7, v205
	ds_read_b128 v[112:115], v128
	ds_read_b128 v[116:119], v128 offset:1024
	ds_read_b128 v[124:127], v128 offset:2048
	ds_read_b128 v[128:131], v128 offset:3072
	ds_read_b128 v[148:151], v160
	ds_read_b128 v[152:155], v160 offset:1024
	ds_read_b128 v[156:159], v160 offset:2048
	ds_read_b128 v[160:163], v160 offset:3072
	s_add_u32 s4, vcc_lo, 0x100000
	s_addc_u32 s5, vcc_hi, 0
	v_lshl_add_u64 v[218:219], s[4:5], 0, v[98:99]
	s_add_i32 m0, s44, 0x4000
	ds_read_b128 v[164:167], v207 offset:32768
	ds_read_b128 v[168:171], v207 offset:33792
	ds_read_b128 v[178:181], v207 offset:34816
	ds_read_b128 v[182:185], v207 offset:35840
	ds_read_b128 v[186:189], v207 offset:36864
	ds_read_b128 v[190:193], v207 offset:37888
	ds_read_b128 v[200:203], v207 offset:38912
	ds_read_b128 v[208:211], v207 offset:39936
	global_load_lds_dwordx4 v[218:219], off
	v_lshl_add_u64 v[218:219], s[4:5], 0, v[174:175]
	s_add_i32 m0, s44, 0x6000
	s_nop 0
	global_load_lds_dwordx4 v[218:219], off
	s_waitcnt vmcnt(8)
	s_waitcnt lgkmcnt(0)
	s_setprio 1
	s_barrier
	v_mfma_f32_16x16x32_bf16 v[144:147], v[112:115], v[164:167], v[144:147]
	v_mfma_f32_16x16x32_bf16 v[140:143], v[124:127], v[164:167], v[140:143]
	v_mfma_f32_16x16x32_bf16 v[120:123], v[112:115], v[178:181], v[120:123]
	v_mfma_f32_16x16x32_bf16 v[108:111], v[124:127], v[178:181], v[108:111]
	v_mfma_f32_16x16x32_bf16 v[94:97], v[112:115], v[186:189], v[94:97]
	v_mfma_f32_16x16x32_bf16 v[90:93], v[124:127], v[186:189], v[90:93]
	v_mfma_f32_16x16x32_bf16 v[78:81], v[112:115], v[200:203], v[78:81]
	v_mfma_f32_16x16x32_bf16 v[74:77], v[124:127], v[200:203], v[74:77]
	v_mfma_f32_16x16x32_bf16 v[144:147], v[116:119], v[168:171], v[144:147]
	v_mfma_f32_16x16x32_bf16 v[140:143], v[128:131], v[168:171], v[140:143]
	v_mfma_f32_16x16x32_bf16 v[120:123], v[116:119], v[182:185], v[120:123]
	v_mfma_f32_16x16x32_bf16 v[108:111], v[128:131], v[182:185], v[108:111]
	v_mfma_f32_16x16x32_bf16 v[94:97], v[116:119], v[190:193], v[94:97]
	v_mfma_f32_16x16x32_bf16 v[90:93], v[128:131], v[190:193], v[90:93]
	v_mfma_f32_16x16x32_bf16 v[78:81], v[116:119], v[208:211], v[78:81]
	v_mfma_f32_16x16x32_bf16 v[74:77], v[128:131], v[208:211], v[74:77]
	s_setprio 0
	s_setprio 1
	v_mfma_f32_16x16x32_bf16 v[136:139], v[148:151], v[164:167], v[136:139]
	v_mfma_f32_16x16x32_bf16 v[132:135], v[156:159], v[164:167], v[132:135]
	v_mfma_f32_16x16x32_bf16 v[104:107], v[148:151], v[178:181], v[104:107]
	v_mfma_f32_16x16x32_bf16 v[100:103], v[156:159], v[178:181], v[100:103]
	v_mfma_f32_16x16x32_bf16 v[86:89], v[148:151], v[186:189], v[86:89]
	v_mfma_f32_16x16x32_bf16 v[82:85], v[156:159], v[186:189], v[82:85]
	v_mfma_f32_16x16x32_bf16 v[70:73], v[148:151], v[200:203], v[70:73]
	v_mfma_f32_16x16x32_bf16 v[66:69], v[156:159], v[200:203], v[66:69]
	v_mfma_f32_16x16x32_bf16 v[136:139], v[152:155], v[168:171], v[136:139]
	v_mfma_f32_16x16x32_bf16 v[132:135], v[160:163], v[168:171], v[132:135]
	v_mfma_f32_16x16x32_bf16 v[104:107], v[152:155], v[182:185], v[104:107]
	v_mfma_f32_16x16x32_bf16 v[100:103], v[160:163], v[182:185], v[100:103]
	v_mfma_f32_16x16x32_bf16 v[86:89], v[152:155], v[190:193], v[86:89]
	v_mfma_f32_16x16x32_bf16 v[82:85], v[160:163], v[190:193], v[82:85]
	v_mfma_f32_16x16x32_bf16 v[70:73], v[152:155], v[208:211], v[70:73]
	v_mfma_f32_16x16x32_bf16 v[66:69], v[160:163], v[208:211], v[66:69]
	s_setprio 0
	s_barrier
	s_add_i32 s4, s6, s91
	v_lshl_add_u64 v[194:195], v[194:195], 0, s[42:43]
	s_mov_b32 m0, s4
	ds_read_b128 v[164:167], v207 offset:49152
	ds_read_b128 v[168:171], v207 offset:50176
	ds_read_b128 v[178:181], v207 offset:51200
	ds_read_b128 v[182:185], v207 offset:52224
	ds_read_b128 v[186:189], v207 offset:53248
	ds_read_b128 v[190:193], v207 offset:54272
	ds_read_b128 v[200:203], v207 offset:55296
	ds_read_b128 v[208:211], v207 offset:56320
	global_load_lds_dwordx4 v[194:195], off
	s_add_i32 m0, s4, 0x2000
	s_add_u32 s4, s78, 0x100080
	v_lshl_add_u64 v[194:195], v[212:213], 0, s[42:43]
	s_addc_u32 s5, s79, 0
	s_add_i32 s6, s7, s91
	global_load_lds_dwordx4 v[194:195], off
	v_lshl_add_u64 v[194:195], s[4:5], 0, v[172:173]
	s_mov_b32 m0, s6
	s_nop 0
	global_load_lds_dwordx4 v[194:195], off
	v_lshl_add_u64 v[194:195], s[4:5], 0, v[176:177]
	s_add_i32 m0, s6, 0x2000
	s_nop 0
	global_load_lds_dwordx4 v[194:195], off
	v_lshl_add_u64 v[194:195], v[214:215], 0, s[42:43]
	s_add_i32 m0, s44, 0x8000
	s_nop 0
	global_load_lds_dwordx4 v[194:195], off
	v_lshl_add_u64 v[194:195], v[216:217], 0, s[42:43]
	s_add_i32 m0, s44, 0xa000
	s_nop 0
	global_load_lds_dwordx4 v[194:195], off
	s_waitcnt vmcnt(8)
	s_waitcnt lgkmcnt(0)
	s_setprio 1
	s_barrier
	v_mfma_f32_16x16x32_bf16 v[62:65], v[112:115], v[164:167], v[62:65]
	v_mfma_f32_16x16x32_bf16 v[58:61], v[124:127], v[164:167], v[58:61]
	v_mfma_f32_16x16x32_bf16 v[46:49], v[112:115], v[178:181], v[46:49]
	v_mfma_f32_16x16x32_bf16 v[42:45], v[124:127], v[178:181], v[42:45]
	v_mfma_f32_16x16x32_bf16 v[30:33], v[112:115], v[186:189], v[30:33]
	v_mfma_f32_16x16x32_bf16 v[26:29], v[124:127], v[186:189], v[26:29]
	v_mfma_f32_16x16x32_bf16 v[14:17], v[112:115], v[200:203], v[14:17]
	v_mfma_f32_16x16x32_bf16 v[10:13], v[124:127], v[200:203], v[10:13]
	v_mfma_f32_16x16x32_bf16 v[62:65], v[116:119], v[168:171], v[62:65]
	v_mfma_f32_16x16x32_bf16 v[58:61], v[128:131], v[168:171], v[58:61]
	v_mfma_f32_16x16x32_bf16 v[46:49], v[116:119], v[182:185], v[46:49]
	v_mfma_f32_16x16x32_bf16 v[42:45], v[128:131], v[182:185], v[42:45]
	v_mfma_f32_16x16x32_bf16 v[30:33], v[116:119], v[190:193], v[30:33]
	v_mfma_f32_16x16x32_bf16 v[26:29], v[128:131], v[190:193], v[26:29]
	v_mfma_f32_16x16x32_bf16 v[14:17], v[116:119], v[208:211], v[14:17]
	v_mfma_f32_16x16x32_bf16 v[10:13], v[128:131], v[208:211], v[10:13]
	s_setprio 0
	s_setprio 1
	v_mfma_f32_16x16x32_bf16 v[54:57], v[148:151], v[164:167], v[54:57]
	v_mfma_f32_16x16x32_bf16 v[50:53], v[156:159], v[164:167], v[50:53]
	v_mfma_f32_16x16x32_bf16 v[38:41], v[148:151], v[178:181], v[38:41]
	v_mfma_f32_16x16x32_bf16 v[34:37], v[156:159], v[178:181], v[34:37]
	v_mfma_f32_16x16x32_bf16 v[22:25], v[148:151], v[186:189], v[22:25]
	v_mfma_f32_16x16x32_bf16 v[18:21], v[156:159], v[186:189], v[18:21]
	v_mfma_f32_16x16x32_bf16 v[6:9], v[148:151], v[200:203], v[6:9]
	v_mfma_f32_16x16x32_bf16 v[2:5], v[156:159], v[200:203], v[2:5]
	v_mfma_f32_16x16x32_bf16 v[54:57], v[152:155], v[168:171], v[54:57]
	v_mfma_f32_16x16x32_bf16 v[50:53], v[160:163], v[168:171], v[50:53]
	v_mfma_f32_16x16x32_bf16 v[38:41], v[152:155], v[182:185], v[38:41]
	v_mfma_f32_16x16x32_bf16 v[34:37], v[160:163], v[182:185], v[34:37]
	v_mfma_f32_16x16x32_bf16 v[22:25], v[152:155], v[190:193], v[22:25]
	v_mfma_f32_16x16x32_bf16 v[18:21], v[160:163], v[190:193], v[18:21]
	v_mfma_f32_16x16x32_bf16 v[6:9], v[152:155], v[208:211], v[6:9]
	v_mfma_f32_16x16x32_bf16 v[2:5], v[160:163], v[208:211], v[2:5]
	s_setprio 0
	s_barrier
	s_mov_b32 s100, 0
	s_add_i32 s95, s95, 2
	s_add_u32 s74, s74, 0x100
	s_addc_u32 s75, s75, 0
	s_add_u32 s71, s71, 0x100
	s_addc_u32 s94, s94, 0
	s_cmp_gt_u32 s95, 61
	s_cbranch_scc0 .LBB0_1116
	s_mov_b32 s100, 1
	s_and_b64 vcc, exec, s[10:11]
	s_cbranch_vccz .LBB0_1119
	s_nop 0

.LBB0_1135:
	s_or_b64 exec, exec, s[70:71]
	s_andn2_b64 vcc, exec, s[30:31]
	s_mov_b64 s[20:21], -1
	s_cbranch_vccnz .LBB0_1105
	s_andn2_b64 vcc, exec, s[14:15]
	s_cbranch_vccnz .LBB0_1104
	s_nop 0
	s_branch .LBB0_1104

.LBB0_1138:
	s_waitcnt vmcnt(0)
	v_readlane_b32 s8, v255, 31
	v_readlane_b32 s74, v255, 33
	v_readlane_b32 s9, v255, 32
	v_readlane_b32 s75, v255, 34
	s_and_b64 vcc, exec, s[10:11]
	s_cbranch_vccz .Lmy_ua_g4a
	s_barrier

.Lmy_sk12:
	s_waitcnt lgkmcnt(0)
	s_setprio 1
	s_barrier
	v_mfma_f32_16x16x32_bf16 v[62:65], v[90:93], v[164:167], v[62:65]
	v_mfma_f32_16x16x32_bf16 v[58:61], v[100:103], v[164:167], v[58:61]
	v_mfma_f32_16x16x32_bf16 v[46:49], v[90:93], v[172:175], v[46:49]
	v_mfma_f32_16x16x32_bf16 v[42:45], v[100:103], v[172:175], v[42:45]
	v_mfma_f32_16x16x32_bf16 v[30:33], v[90:93], v[180:183], v[30:33]
	v_mfma_f32_16x16x32_bf16 v[26:29], v[100:103], v[180:183], v[26:29]
	v_mfma_f32_16x16x32_bf16 v[14:17], v[90:93], v[188:191], v[14:17]
	v_mfma_f32_16x16x32_bf16 v[10:13], v[100:103], v[188:191], v[10:13]
	v_mfma_f32_16x16x32_bf16 v[62:65], v[94:97], v[168:171], v[62:65]
	v_mfma_f32_16x16x32_bf16 v[58:61], v[104:107], v[168:171], v[58:61]
	v_mfma_f32_16x16x32_bf16 v[46:49], v[94:97], v[176:179], v[46:49]
	v_mfma_f32_16x16x32_bf16 v[42:45], v[104:107], v[176:179], v[42:45]
	v_mfma_f32_16x16x32_bf16 v[30:33], v[94:97], v[184:187], v[30:33]
	v_mfma_f32_16x16x32_bf16 v[26:29], v[104:107], v[184:187], v[26:29]
	v_mfma_f32_16x16x32_bf16 v[14:17], v[94:97], v[192:195], v[14:17]
	v_mfma_f32_16x16x32_bf16 v[10:13], v[104:107], v[192:195], v[10:13]
	s_setprio 0
	s_setprio 1
	v_mfma_f32_16x16x32_bf16 v[54:57], v[108:111], v[164:167], v[54:57]
	v_mfma_f32_16x16x32_bf16 v[50:53], v[120:123], v[164:167], v[50:53]
	v_mfma_f32_16x16x32_bf16 v[38:41], v[108:111], v[172:175], v[38:41]
	v_mfma_f32_16x16x32_bf16 v[34:37], v[120:123], v[172:175], v[34:37]
	v_mfma_f32_16x16x32_bf16 v[22:25], v[108:111], v[180:183], v[22:25]
	v_mfma_f32_16x16x32_bf16 v[18:21], v[120:123], v[180:183], v[18:21]
	v_mfma_f32_16x16x32_bf16 v[6:9], v[108:111], v[188:191], v[6:9]
	v_mfma_f32_16x16x32_bf16 v[2:5], v[120:123], v[188:191], v[2:5]
	v_mfma_f32_16x16x32_bf16 v[54:57], v[112:115], v[168:171], v[54:57]
	v_mfma_f32_16x16x32_bf16 v[50:53], v[128:131], v[168:171], v[50:53]
	v_mfma_f32_16x16x32_bf16 v[38:41], v[112:115], v[176:179], v[38:41]
	v_mfma_f32_16x16x32_bf16 v[34:37], v[128:131], v[176:179], v[34:37]
	v_mfma_f32_16x16x32_bf16 v[22:25], v[112:115], v[184:187], v[22:25]
	v_mfma_f32_16x16x32_bf16 v[18:21], v[128:131], v[184:187], v[18:21]
	v_mfma_f32_16x16x32_bf16 v[6:9], v[112:115], v[192:195], v[6:9]
	v_mfma_f32_16x16x32_bf16 v[2:5], v[128:131], v[192:195], v[2:5]
	s_setprio 0
	s_barrier
	s_add_i32 s6, 0, 0x18000
	s_add_i32 s7, 0, 0x1c000
	v_add_u32_e32 v104, s6, v239
	v_add_u32_e32 v128, s7, v239
	ds_read_b128 v[90:93], v104
	ds_read_b128 v[94:97], v104 offset:1024
	ds_read_b128 v[100:103], v104 offset:2048
	ds_read_b128 v[104:107], v104 offset:3072
	ds_read_b128 v[108:111], v128
	ds_read_b128 v[112:115], v128 offset:1024
	ds_read_b128 v[120:123], v128 offset:2048
	ds_read_b128 v[128:131], v128 offset:3072
	s_add_u32 s4, s78, 0x100000
	s_addc_u32 s5, s79, 0
	v_lshl_add_u64 v[214:215], s[4:5], 0, v[98:99]
	s_add_i32 m0, s44, 0x4000
	ds_read_b128 v[164:167], v241 offset:32768
	ds_read_b128 v[168:171], v241 offset:33792
	ds_read_b128 v[172:175], v241 offset:34816
	ds_read_b128 v[176:179], v241 offset:35840
	ds_read_b128 v[180:183], v241 offset:36864
	ds_read_b128 v[184:187], v241 offset:37888
	ds_read_b128 v[188:191], v241 offset:38912
	ds_read_b128 v[192:195], v241 offset:39936
	global_load_lds_dwordx4 v[214:215], off
	v_lshl_add_u64 v[214:215], s[4:5], 0, v[206:207]
	s_add_i32 m0, s44, 0x6000
	s_nop 0
	global_load_lds_dwordx4 v[214:215], off
	s_waitcnt vmcnt(8)
	s_waitcnt lgkmcnt(0)
	s_setprio 1
	s_barrier
	v_mfma_f32_16x16x32_bf16 v[160:163], v[90:93], v[164:167], v[160:163]
	v_mfma_f32_16x16x32_bf16 v[156:159], v[100:103], v[164:167], v[156:159]
	v_mfma_f32_16x16x32_bf16 v[144:147], v[90:93], v[172:175], v[144:147]
	v_mfma_f32_16x16x32_bf16 v[140:143], v[100:103], v[172:175], v[140:143]
	v_mfma_f32_16x16x32_bf16 v[124:127], v[90:93], v[180:183], v[124:127]
	v_mfma_f32_16x16x32_bf16 v[116:119], v[100:103], v[180:183], v[116:119]
	v_mfma_f32_16x16x32_bf16 v[78:81], v[90:93], v[188:191], v[78:81]
	v_mfma_f32_16x16x32_bf16 v[74:77], v[100:103], v[188:191], v[74:77]
	v_mfma_f32_16x16x32_bf16 v[160:163], v[94:97], v[168:171], v[160:163]
	v_mfma_f32_16x16x32_bf16 v[156:159], v[104:107], v[168:171], v[156:159]
	v_mfma_f32_16x16x32_bf16 v[144:147], v[94:97], v[176:179], v[144:147]
	v_mfma_f32_16x16x32_bf16 v[140:143], v[104:107], v[176:179], v[140:143]
	v_mfma_f32_16x16x32_bf16 v[124:127], v[94:97], v[184:187], v[124:127]
	v_mfma_f32_16x16x32_bf16 v[116:119], v[104:107], v[184:187], v[116:119]
	v_mfma_f32_16x16x32_bf16 v[78:81], v[94:97], v[192:195], v[78:81]
	v_mfma_f32_16x16x32_bf16 v[74:77], v[104:107], v[192:195], v[74:77]
	s_setprio 0
	s_setprio 1
	v_mfma_f32_16x16x32_bf16 v[152:155], v[108:111], v[164:167], v[152:155]
	v_mfma_f32_16x16x32_bf16 v[148:151], v[120:123], v[164:167], v[148:151]
	v_mfma_f32_16x16x32_bf16 v[136:139], v[108:111], v[172:175], v[136:139]
	v_mfma_f32_16x16x32_bf16 v[132:135], v[120:123], v[172:175], v[132:135]
	v_mfma_f32_16x16x32_bf16 v[86:89], v[108:111], v[180:183], v[86:89]
	v_mfma_f32_16x16x32_bf16 v[82:85], v[120:123], v[180:183], v[82:85]
	v_mfma_f32_16x16x32_bf16 v[70:73], v[108:111], v[188:191], v[70:73]
	v_mfma_f32_16x16x32_bf16 v[66:69], v[120:123], v[188:191], v[66:69]
	v_mfma_f32_16x16x32_bf16 v[152:155], v[112:115], v[168:171], v[152:155]
	v_mfma_f32_16x16x32_bf16 v[148:151], v[128:131], v[168:171], v[148:151]
	v_mfma_f32_16x16x32_bf16 v[136:139], v[112:115], v[176:179], v[136:139]
	v_mfma_f32_16x16x32_bf16 v[132:135], v[128:131], v[176:179], v[132:135]
	v_mfma_f32_16x16x32_bf16 v[86:89], v[112:115], v[184:187], v[86:89]
	v_mfma_f32_16x16x32_bf16 v[82:85], v[128:131], v[184:187], v[82:85]
	v_mfma_f32_16x16x32_bf16 v[70:73], v[112:115], v[192:195], v[70:73]
	v_mfma_f32_16x16x32_bf16 v[66:69], v[128:131], v[192:195], v[66:69]
	s_setprio 0
	s_barrier
	s_add_i32 s4, s6, s91
	v_lshl_add_u64 v[200:201], v[200:201], 0, s[42:43]
	s_mov_b32 m0, s4
	ds_read_b128 v[164:167], v241 offset:49152
	ds_read_b128 v[168:171], v241 offset:50176
	ds_read_b128 v[172:175], v241 offset:51200
	ds_read_b128 v[176:179], v241 offset:52224
	ds_read_b128 v[180:183], v241 offset:53248
	ds_read_b128 v[184:187], v241 offset:54272
	ds_read_b128 v[188:191], v241 offset:55296
	ds_read_b128 v[192:195], v241 offset:56320
	global_load_lds_dwordx4 v[200:201], off
	s_add_i32 m0, s4, 0x2000
	s_add_u32 s4, s74, 0x100080
	v_lshl_add_u64 v[200:201], v[202:203], 0, s[42:43]
	s_addc_u32 s5, s75, 0
	s_add_i32 s6, s7, s91
	global_load_lds_dwordx4 v[200:201], off
	v_lshl_add_u64 v[200:201], s[4:5], 0, v[204:205]
	s_mov_b32 m0, s6
	s_nop 0
	global_load_lds_dwordx4 v[200:201], off
	v_lshl_add_u64 v[200:201], s[4:5], 0, v[208:209]
	s_add_i32 m0, s6, 0x2000
	s_nop 0
	global_load_lds_dwordx4 v[200:201], off
	v_lshl_add_u64 v[200:201], v[210:211], 0, s[42:43]
	s_add_i32 m0, s44, 0x8000
	s_nop 0
	global_load_lds_dwordx4 v[200:201], off
	v_lshl_add_u64 v[200:201], v[212:213], 0, s[42:43]
	s_add_i32 m0, s44, 0xa000
	s_nop 0
	global_load_lds_dwordx4 v[200:201], off
	s_waitcnt vmcnt(8)
	s_waitcnt lgkmcnt(0)
	s_setprio 1
	s_barrier
	v_mfma_f32_16x16x32_bf16 v[62:65], v[90:93], v[164:167], v[62:65]
	v_mfma_f32_16x16x32_bf16 v[58:61], v[100:103], v[164:167], v[58:61]
	v_mfma_f32_16x16x32_bf16 v[46:49], v[90:93], v[172:175], v[46:49]
	v_mfma_f32_16x16x32_bf16 v[42:45], v[100:103], v[172:175], v[42:45]
	v_mfma_f32_16x16x32_bf16 v[30:33], v[90:93], v[180:183], v[30:33]
	v_mfma_f32_16x16x32_bf16 v[26:29], v[100:103], v[180:183], v[26:29]
	v_mfma_f32_16x16x32_bf16 v[14:17], v[90:93], v[188:191], v[14:17]
	v_mfma_f32_16x16x32_bf16 v[10:13], v[100:103], v[188:191], v[10:13]
	v_mfma_f32_16x16x32_bf16 v[62:65], v[94:97], v[168:171], v[62:65]
	v_mfma_f32_16x16x32_bf16 v[58:61], v[104:107], v[168:171], v[58:61]
	v_mfma_f32_16x16x32_bf16 v[46:49], v[94:97], v[176:179], v[46:49]
	v_mfma_f32_16x16x32_bf16 v[42:45], v[104:107], v[176:179], v[42:45]
	v_mfma_f32_16x16x32_bf16 v[30:33], v[94:97], v[184:187], v[30:33]
	v_mfma_f32_16x16x32_bf16 v[26:29], v[104:107], v[184:187], v[26:29]
	v_mfma_f32_16x16x32_bf16 v[14:17], v[94:97], v[192:195], v[14:17]
	v_mfma_f32_16x16x32_bf16 v[10:13], v[104:107], v[192:195], v[10:13]
	s_setprio 0
	s_setprio 1
	v_mfma_f32_16x16x32_bf16 v[54:57], v[108:111], v[164:167], v[54:57]
	v_mfma_f32_16x16x32_bf16 v[50:53], v[120:123], v[164:167], v[50:53]
	v_mfma_f32_16x16x32_bf16 v[38:41], v[108:111], v[172:175], v[38:41]
	v_mfma_f32_16x16x32_bf16 v[34:37], v[120:123], v[172:175], v[34:37]
	v_mfma_f32_16x16x32_bf16 v[22:25], v[108:111], v[180:183], v[22:25]
	v_mfma_f32_16x16x32_bf16 v[18:21], v[120:123], v[180:183], v[18:21]
	v_mfma_f32_16x16x32_bf16 v[6:9], v[108:111], v[188:191], v[6:9]
	v_mfma_f32_16x16x32_bf16 v[2:5], v[120:123], v[188:191], v[2:5]
	v_mfma_f32_16x16x32_bf16 v[54:57], v[112:115], v[168:171], v[54:57]
	v_mfma_f32_16x16x32_bf16 v[50:53], v[128:131], v[168:171], v[50:53]
	v_mfma_f32_16x16x32_bf16 v[38:41], v[112:115], v[176:179], v[38:41]
	v_mfma_f32_16x16x32_bf16 v[34:37], v[128:131], v[176:179], v[34:37]
	v_mfma_f32_16x16x32_bf16 v[22:25], v[112:115], v[184:187], v[22:25]
	v_mfma_f32_16x16x32_bf16 v[18:21], v[128:131], v[184:187], v[18:21]
	v_mfma_f32_16x16x32_bf16 v[6:9], v[112:115], v[192:195], v[6:9]
	v_mfma_f32_16x16x32_bf16 v[2:5], v[128:131], v[192:195], v[2:5]
	s_setprio 0
	s_barrier
	s_mov_b32 s100, 0
	s_add_i32 s95, s95, 2
	s_add_u32 s70, s70, 0x100
	s_addc_u32 s71, s71, 0
	s_add_u32 s69, s69, 0x100
	s_addc_u32 s94, s94, 0
	s_cmp_gt_u32 s95, 61
	s_cbranch_scc0 .LBB0_1172
	s_mov_b32 s100, 1
	s_and_b64 vcc, exec, s[10:11]
	s_cbranch_vccz .LBB0_1175
	s_nop 0

.LBB0_1191:
	s_or_b64 exec, exec, s[68:69]
	s_andn2_b64 vcc, exec, s[30:31]
	s_mov_b64 s[30:31], -1
	s_cbranch_vccnz .LBB0_1161
	s_andn2_b64 vcc, exec, s[12:13]
	s_cbranch_vccnz .LBB0_1160
	s_nop 0
	s_branch .LBB0_1160

.LBB0_1195:
	s_waitcnt vmcnt(0)
	v_readlane_b32 s8, v255, 31
	v_readlane_b32 s74, v255, 33
	v_readlane_b32 s70, v255, 37
	v_readlane_b32 s9, v255, 32
	v_readlane_b32 s75, v255, 34
	v_readlane_b32 s77, v255, 36
	v_readlane_b32 s71, v255, 38
	s_and_b64 vcc, exec, s[10:11]
	s_cbranch_vccz .Lmy_ua_g4b
	s_barrier
